# dependent packed ops interleaved (p, vk, p, tw)
# baseline (speedup 1.0000x reference)
.LBB0_682:
	s_bitcmp1_b32 s30, 0
	s_cselect_b32 s6, 0xe000, 0
	s_add_i32 s6, s6, 0
	v_add_u32_e32 v90, s6, v58
	v_sub_u32_e32 v88, v90, v61
	v_add_u32_e32 v89, s6, v86
	ds_read_b128 v[4:7], v90 offset:0x4000
	ds_read_b128 v[8:11], v90 offset:0x0
	ds_read2st64_b32 v[108:109], v89 offset0:192 offset1:193
	ds_read2st64_b64 v[100:103], v88 offset0:64 offset1:65
	ds_read_b128 v[112:115], v90 offset:0x4200
	ds_read_b128 v[96:99], v90 offset:0x200
	ds_read_b128 v[120:123], v90 offset:0x4400
	ds_read_b128 v[124:127], v90 offset:0x400
	v_mov_b32_e32 v93, v91
	s_waitcnt lgkmcnt(5)
	v_pk_mul_f32 v[0:1], v[52:53], v[4:5] op_sel_hi:[0,1]
	v_pk_mul_f32 v[10:11], v[108:109], v[10:11] op_sel_hi:[0,1]
	v_pk_fma_f32 v[0:1], v[52:53], v[6:7], v[0:1] op_sel:[1,0,0]
	v_pk_fma_f32 v[54:55], v[52:53], v[8:9], v[10:11]
	s_nop 0
	ds_read_b128 v[4:7], v90 offset:0x4600
	v_add_f32_dpp v0, v0, v0 quad_perm:[1,0,3,2] row_mask:0xf bank_mask:0xf bound_ctrl:1
	v_add_f32_dpp v1, v1, v1 quad_perm:[1,0,3,2] row_mask:0xf bank_mask:0xf bound_ctrl:1
	s_nop 0
	ds_read_b128 v[8:11], v90 offset:0x600
	v_add_f32_dpp v0, v0, v0 quad_perm:[2,3,0,1] row_mask:0xf bank_mask:0xf bound_ctrl:1
	s_nop 0
	ds_read2st64_b32 v[110:111], v89 offset0:194 offset1:195
	ds_read2st64_b64 v[104:107], v88 offset0:66 offset1:67
	v_add_f32_dpp v0, v0, v0 row_half_mirror row_mask:0xf bank_mask:0xf bound_ctrl:1
	s_nop 0
	s_waitcnt lgkmcnt(6)
	v_add_f32_dpp v2, v0, v0 row_mirror row_mask:0xf bank_mask:0xf bound_ctrl:1
	v_add_f32_dpp v0, v0, v0 row_mirror row_mask:0xf bank_mask:0xf bound_ctrl:1
	s_nop 1
	v_permlane16_swap_b32_e32 v0, v2
	v_add_f32_e32 v0, v0, v2
	v_pk_fma_f32 v[52:53], v[100:101], v[0:1], v[54:55] op_sel_hi:[1,0,1]
	v_pk_mul_f32 v[118:119], v[52:53], v[112:113] op_sel_hi:[0,1]
	v_pk_mul_f32 v[98:99], v[108:109], v[98:99] op_sel:[1,0]
	v_pk_fma_f32 v[118:119], v[52:53], v[114:115], v[118:119] op_sel:[1,0,0]
	v_pk_fma_f32 v[54:55], v[52:53], v[96:97], v[98:99]
	s_nop 0
	ds_read_b128 v[112:115], v90 offset:0x4800
	v_add_f32_dpp v118, v118, v118 quad_perm:[1,0,3,2] row_mask:0xf bank_mask:0xf bound_ctrl:1
	v_add_f32_dpp v119, v119, v119 quad_perm:[1,0,3,2] row_mask:0xf bank_mask:0xf bound_ctrl:1
	s_nop 0
	ds_read_b128 v[96:99], v90 offset:0x800
	v_add_f32_dpp v118, v118, v118 quad_perm:[2,3,0,1] row_mask:0xf bank_mask:0xf bound_ctrl:1
	s_nop 0
	ds_write2_b32 v93, v1, v119 offset0:0 offset1:36
	v_add_f32_dpp v118, v118, v118 row_half_mirror row_mask:0xf bank_mask:0xf bound_ctrl:1
	s_nop 0
	s_waitcnt lgkmcnt(4)
	v_add_f32_dpp v2, v118, v118 row_mirror row_mask:0xf bank_mask:0xf bound_ctrl:1
	v_add_f32_dpp v118, v118, v118 row_mirror row_mask:0xf bank_mask:0xf bound_ctrl:1
	s_nop 1
	v_permlane16_swap_b32_e32 v118, v2
	v_add_f32_e32 v118, v118, v2
	v_pk_fma_f32 v[52:53], v[102:103], v[118:119], v[54:55] op_sel_hi:[1,0,1]
	v_pk_mul_f32 v[0:1], v[52:53], v[120:121] op_sel_hi:[0,1]
	v_pk_mul_f32 v[126:127], v[110:111], v[126:127] op_sel_hi:[0,1]
	v_pk_fma_f32 v[0:1], v[52:53], v[122:123], v[0:1] op_sel:[1,0,0]
	v_pk_fma_f32 v[54:55], v[52:53], v[124:125], v[126:127]
	s_nop 0
	ds_read_b128 v[120:123], v90 offset:0x4a00
	v_add_f32_dpp v0, v0, v0 quad_perm:[1,0,3,2] row_mask:0xf bank_mask:0xf bound_ctrl:1
	v_add_f32_dpp v1, v1, v1 quad_perm:[1,0,3,2] row_mask:0xf bank_mask:0xf bound_ctrl:1
	s_nop 0
	ds_read_b128 v[124:127], v90 offset:0xa00
	v_add_f32_dpp v0, v0, v0 quad_perm:[2,3,0,1] row_mask:0xf bank_mask:0xf bound_ctrl:1
	s_nop 0
	ds_read2st64_b32 v[108:109], v89 offset0:196 offset1:197
	ds_read2st64_b64 v[100:103], v88 offset0:68 offset1:69
	v_add_f32_dpp v0, v0, v0 row_half_mirror row_mask:0xf bank_mask:0xf bound_ctrl:1
	s_nop 0
	s_waitcnt lgkmcnt(7)
	v_add_f32_dpp v2, v0, v0 row_mirror row_mask:0xf bank_mask:0xf bound_ctrl:1
	v_add_f32_dpp v0, v0, v0 row_mirror row_mask:0xf bank_mask:0xf bound_ctrl:1
	s_nop 1
	v_permlane16_swap_b32_e32 v0, v2
	v_add_f32_e32 v0, v0, v2
	v_pk_fma_f32 v[52:53], v[104:105], v[0:1], v[54:55] op_sel_hi:[1,0,1]
	v_pk_mul_f32 v[118:119], v[52:53], v[4:5] op_sel_hi:[0,1]
	v_pk_mul_f32 v[10:11], v[110:111], v[10:11] op_sel:[1,0]
	v_pk_fma_f32 v[118:119], v[52:53], v[6:7], v[118:119] op_sel:[1,0,0]
	v_pk_fma_f32 v[54:55], v[52:53], v[8:9], v[10:11]
	s_nop 0
	ds_read_b128 v[4:7], v90 offset:0x4c00
	v_add_f32_dpp v118, v118, v118 quad_perm:[1,0,3,2] row_mask:0xf bank_mask:0xf bound_ctrl:1
	v_add_f32_dpp v119, v119, v119 quad_perm:[1,0,3,2] row_mask:0xf bank_mask:0xf bound_ctrl:1
	s_nop 0
	ds_read_b128 v[8:11], v90 offset:0xc00
	v_add_f32_dpp v118, v118, v118 quad_perm:[2,3,0,1] row_mask:0xf bank_mask:0xf bound_ctrl:1
	s_nop 0
	ds_write2_b32 v93, v1, v119 offset0:72 offset1:108
	v_add_f32_dpp v118, v118, v118 row_half_mirror row_mask:0xf bank_mask:0xf bound_ctrl:1
	s_nop 0
	s_waitcnt lgkmcnt(4)
	v_add_f32_dpp v2, v118, v118 row_mirror row_mask:0xf bank_mask:0xf bound_ctrl:1
	v_add_f32_dpp v118, v118, v118 row_mirror row_mask:0xf bank_mask:0xf bound_ctrl:1
	s_nop 1
	v_permlane16_swap_b32_e32 v118, v2
	v_add_f32_e32 v118, v118, v2
	v_pk_fma_f32 v[52:53], v[106:107], v[118:119], v[54:55] op_sel_hi:[1,0,1]
	v_pk_mul_f32 v[0:1], v[52:53], v[112:113] op_sel_hi:[0,1]
	v_pk_mul_f32 v[98:99], v[108:109], v[98:99] op_sel_hi:[0,1]
	v_pk_fma_f32 v[0:1], v[52:53], v[114:115], v[0:1] op_sel:[1,0,0]
	v_pk_fma_f32 v[54:55], v[52:53], v[96:97], v[98:99]
	s_nop 0
	ds_read_b128 v[112:115], v90 offset:0x4e00
	v_add_f32_dpp v0, v0, v0 quad_perm:[1,0,3,2] row_mask:0xf bank_mask:0xf bound_ctrl:1
	v_add_f32_dpp v1, v1, v1 quad_perm:[1,0,3,2] row_mask:0xf bank_mask:0xf bound_ctrl:1
	s_nop 0
	ds_read_b128 v[96:99], v90 offset:0xe00
	v_add_f32_dpp v0, v0, v0 quad_perm:[2,3,0,1] row_mask:0xf bank_mask:0xf bound_ctrl:1
	s_nop 0
	ds_read2st64_b32 v[110:111], v89 offset0:198 offset1:199
	ds_read2st64_b64 v[104:107], v88 offset0:70 offset1:71
	v_add_f32_dpp v0, v0, v0 row_half_mirror row_mask:0xf bank_mask:0xf bound_ctrl:1
	s_nop 0
	s_waitcnt lgkmcnt(7)
	v_add_f32_dpp v2, v0, v0 row_mirror row_mask:0xf bank_mask:0xf bound_ctrl:1
	v_add_f32_dpp v0, v0, v0 row_mirror row_mask:0xf bank_mask:0xf bound_ctrl:1
	s_nop 1
	v_permlane16_swap_b32_e32 v0, v2
	v_add_f32_e32 v0, v0, v2
	v_pk_fma_f32 v[52:53], v[100:101], v[0:1], v[54:55] op_sel_hi:[1,0,1]
	v_pk_mul_f32 v[118:119], v[52:53], v[120:121] op_sel_hi:[0,1]
	v_pk_mul_f32 v[126:127], v[108:109], v[126:127] op_sel:[1,0]
	v_pk_fma_f32 v[118:119], v[52:53], v[122:123], v[118:119] op_sel:[1,0,0]
	v_pk_fma_f32 v[54:55], v[52:53], v[124:125], v[126:127]
	s_nop 0
	ds_read_b128 v[120:123], v90 offset:0x5000
	v_add_f32_dpp v118, v118, v118 quad_perm:[1,0,3,2] row_mask:0xf bank_mask:0xf bound_ctrl:1
	v_add_f32_dpp v119, v119, v119 quad_perm:[1,0,3,2] row_mask:0xf bank_mask:0xf bound_ctrl:1
	s_nop 0
	ds_read_b128 v[124:127], v90 offset:0x1000
	v_add_f32_dpp v118, v118, v118 quad_perm:[2,3,0,1] row_mask:0xf bank_mask:0xf bound_ctrl:1
	s_nop 0
	ds_write2_b32 v93, v1, v119 offset0:144 offset1:180
	v_add_f32_dpp v118, v118, v118 row_half_mirror row_mask:0xf bank_mask:0xf bound_ctrl:1
	s_nop 0
	s_waitcnt lgkmcnt(4)
	v_add_f32_dpp v2, v118, v118 row_mirror row_mask:0xf bank_mask:0xf bound_ctrl:1
	v_add_f32_dpp v118, v118, v118 row_mirror row_mask:0xf bank_mask:0xf bound_ctrl:1
	s_nop 1
	v_permlane16_swap_b32_e32 v118, v2
	v_add_f32_e32 v118, v118, v2
	v_pk_fma_f32 v[52:53], v[102:103], v[118:119], v[54:55] op_sel_hi:[1,0,1]
	v_pk_mul_f32 v[0:1], v[52:53], v[4:5] op_sel_hi:[0,1]
	v_pk_mul_f32 v[10:11], v[110:111], v[10:11] op_sel_hi:[0,1]
	v_pk_fma_f32 v[0:1], v[52:53], v[6:7], v[0:1] op_sel:[1,0,0]
	v_pk_fma_f32 v[54:55], v[52:53], v[8:9], v[10:11]
	s_nop 0
	ds_read_b128 v[4:7], v90 offset:0x5200
	v_add_f32_dpp v0, v0, v0 quad_perm:[1,0,3,2] row_mask:0xf bank_mask:0xf bound_ctrl:1
	v_add_f32_dpp v1, v1, v1 quad_perm:[1,0,3,2] row_mask:0xf bank_mask:0xf bound_ctrl:1
	s_nop 0
	ds_read_b128 v[8:11], v90 offset:0x1200
	v_add_f32_dpp v0, v0, v0 quad_perm:[2,3,0,1] row_mask:0xf bank_mask:0xf bound_ctrl:1
	s_nop 0
	ds_read2st64_b32 v[108:109], v89 offset0:200 offset1:201
	ds_read2st64_b64 v[100:103], v88 offset0:72 offset1:73
	v_add_f32_dpp v0, v0, v0 row_half_mirror row_mask:0xf bank_mask:0xf bound_ctrl:1
	s_nop 0
	s_waitcnt lgkmcnt(7)
	v_add_f32_dpp v2, v0, v0 row_mirror row_mask:0xf bank_mask:0xf bound_ctrl:1
	v_add_f32_dpp v0, v0, v0 row_mirror row_mask:0xf bank_mask:0xf bound_ctrl:1
	s_nop 1
	v_permlane16_swap_b32_e32 v0, v2
	v_add_f32_e32 v0, v0, v2
	v_pk_fma_f32 v[52:53], v[104:105], v[0:1], v[54:55] op_sel_hi:[1,0,1]
	v_pk_mul_f32 v[118:119], v[52:53], v[112:113] op_sel_hi:[0,1]
	v_pk_mul_f32 v[98:99], v[110:111], v[98:99] op_sel:[1,0]
	v_pk_fma_f32 v[118:119], v[52:53], v[114:115], v[118:119] op_sel:[1,0,0]
	v_pk_fma_f32 v[54:55], v[52:53], v[96:97], v[98:99]
	s_nop 0
	ds_read_b128 v[112:115], v90 offset:0x5400
	v_add_f32_dpp v118, v118, v118 quad_perm:[1,0,3,2] row_mask:0xf bank_mask:0xf bound_ctrl:1
	v_add_f32_dpp v119, v119, v119 quad_perm:[1,0,3,2] row_mask:0xf bank_mask:0xf bound_ctrl:1
	s_nop 0
	ds_read_b128 v[96:99], v90 offset:0x1400
	v_add_f32_dpp v118, v118, v118 quad_perm:[2,3,0,1] row_mask:0xf bank_mask:0xf bound_ctrl:1
	s_nop 0
	ds_write2_b32 v93, v1, v119 offset0:216 offset1:252
	v_add_f32_dpp v118, v118, v118 row_half_mirror row_mask:0xf bank_mask:0xf bound_ctrl:1
	s_nop 0
	s_waitcnt lgkmcnt(4)
	v_add_f32_dpp v2, v118, v118 row_mirror row_mask:0xf bank_mask:0xf bound_ctrl:1
	v_add_f32_dpp v118, v118, v118 row_mirror row_mask:0xf bank_mask:0xf bound_ctrl:1
	s_nop 1
	v_permlane16_swap_b32_e32 v118, v2
	v_add_f32_e32 v118, v118, v2
	v_pk_fma_f32 v[52:53], v[106:107], v[118:119], v[54:55] op_sel_hi:[1,0,1]
	v_pk_mul_f32 v[0:1], v[52:53], v[120:121] op_sel_hi:[0,1]
	v_pk_mul_f32 v[126:127], v[108:109], v[126:127] op_sel_hi:[0,1]
	v_pk_fma_f32 v[0:1], v[52:53], v[122:123], v[0:1] op_sel:[1,0,0]
	v_pk_fma_f32 v[54:55], v[52:53], v[124:125], v[126:127]
	s_nop 0
	ds_read_b128 v[120:123], v90 offset:0x5600
	v_add_f32_dpp v0, v0, v0 quad_perm:[1,0,3,2] row_mask:0xf bank_mask:0xf bound_ctrl:1
	v_add_f32_dpp v1, v1, v1 quad_perm:[1,0,3,2] row_mask:0xf bank_mask:0xf bound_ctrl:1
	s_nop 0
	ds_read_b128 v[124:127], v90 offset:0x1600
	v_add_f32_dpp v0, v0, v0 quad_perm:[2,3,0,1] row_mask:0xf bank_mask:0xf bound_ctrl:1
	s_nop 0
	ds_read2st64_b32 v[110:111], v89 offset0:202 offset1:203
	ds_read2st64_b64 v[104:107], v88 offset0:74 offset1:75
	v_add_f32_dpp v0, v0, v0 row_half_mirror row_mask:0xf bank_mask:0xf bound_ctrl:1
	v_add_u32_e32 v93, 0x480, v93
	s_waitcnt lgkmcnt(7)
	v_add_f32_dpp v2, v0, v0 row_mirror row_mask:0xf bank_mask:0xf bound_ctrl:1
	v_add_f32_dpp v0, v0, v0 row_mirror row_mask:0xf bank_mask:0xf bound_ctrl:1
	s_nop 1
	v_permlane16_swap_b32_e32 v0, v2
	v_add_f32_e32 v0, v0, v2
	v_pk_fma_f32 v[52:53], v[100:101], v[0:1], v[54:55] op_sel_hi:[1,0,1]
	v_pk_mul_f32 v[118:119], v[52:53], v[4:5] op_sel_hi:[0,1]
	v_pk_mul_f32 v[10:11], v[108:109], v[10:11] op_sel:[1,0]
	v_pk_fma_f32 v[118:119], v[52:53], v[6:7], v[118:119] op_sel:[1,0,0]
	v_pk_fma_f32 v[54:55], v[52:53], v[8:9], v[10:11]
	s_nop 0
	ds_read_b128 v[4:7], v90 offset:0x5800
	v_add_f32_dpp v118, v118, v118 quad_perm:[1,0,3,2] row_mask:0xf bank_mask:0xf bound_ctrl:1
	v_add_f32_dpp v119, v119, v119 quad_perm:[1,0,3,2] row_mask:0xf bank_mask:0xf bound_ctrl:1
	s_nop 0
	ds_read_b128 v[8:11], v90 offset:0x1800
	v_add_f32_dpp v118, v118, v118 quad_perm:[2,3,0,1] row_mask:0xf bank_mask:0xf bound_ctrl:1
	s_nop 0
	ds_write2_b32 v93, v1, v119 offset0:0 offset1:36
	v_add_f32_dpp v118, v118, v118 row_half_mirror row_mask:0xf bank_mask:0xf bound_ctrl:1
	s_nop 0
	s_waitcnt lgkmcnt(4)
	v_add_f32_dpp v2, v118, v118 row_mirror row_mask:0xf bank_mask:0xf bound_ctrl:1
	v_add_f32_dpp v118, v118, v118 row_mirror row_mask:0xf bank_mask:0xf bound_ctrl:1
	s_nop 1
	v_permlane16_swap_b32_e32 v118, v2
	v_add_f32_e32 v118, v118, v2
	v_pk_fma_f32 v[52:53], v[102:103], v[118:119], v[54:55] op_sel_hi:[1,0,1]
	v_pk_mul_f32 v[0:1], v[52:53], v[112:113] op_sel_hi:[0,1]
	v_pk_mul_f32 v[98:99], v[110:111], v[98:99] op_sel_hi:[0,1]
	v_pk_fma_f32 v[0:1], v[52:53], v[114:115], v[0:1] op_sel:[1,0,0]
	v_pk_fma_f32 v[54:55], v[52:53], v[96:97], v[98:99]
	s_nop 0
	ds_read_b128 v[112:115], v90 offset:0x5a00
	v_add_f32_dpp v0, v0, v0 quad_perm:[1,0,3,2] row_mask:0xf bank_mask:0xf bound_ctrl:1
	v_add_f32_dpp v1, v1, v1 quad_perm:[1,0,3,2] row_mask:0xf bank_mask:0xf bound_ctrl:1
	s_nop 0
	ds_read_b128 v[96:99], v90 offset:0x1a00
	v_add_f32_dpp v0, v0, v0 quad_perm:[2,3,0,1] row_mask:0xf bank_mask:0xf bound_ctrl:1
	s_nop 0
	ds_read2st64_b32 v[108:109], v89 offset0:204 offset1:205
	ds_read2st64_b64 v[100:103], v88 offset0:76 offset1:77
	v_add_f32_dpp v0, v0, v0 row_half_mirror row_mask:0xf bank_mask:0xf bound_ctrl:1
	s_nop 0
	s_waitcnt lgkmcnt(7)
	v_add_f32_dpp v2, v0, v0 row_mirror row_mask:0xf bank_mask:0xf bound_ctrl:1
	v_add_f32_dpp v0, v0, v0 row_mirror row_mask:0xf bank_mask:0xf bound_ctrl:1
	s_nop 1
	v_permlane16_swap_b32_e32 v0, v2
	v_add_f32_e32 v0, v0, v2
	v_pk_fma_f32 v[52:53], v[104:105], v[0:1], v[54:55] op_sel_hi:[1,0,1]
	v_pk_mul_f32 v[118:119], v[52:53], v[120:121] op_sel_hi:[0,1]
	v_pk_mul_f32 v[126:127], v[110:111], v[126:127] op_sel:[1,0]
	v_pk_fma_f32 v[118:119], v[52:53], v[122:123], v[118:119] op_sel:[1,0,0]
	v_pk_fma_f32 v[54:55], v[52:53], v[124:125], v[126:127]
	s_nop 0
	ds_read_b128 v[120:123], v90 offset:0x5c00
	v_add_f32_dpp v118, v118, v118 quad_perm:[1,0,3,2] row_mask:0xf bank_mask:0xf bound_ctrl:1
	v_add_f32_dpp v119, v119, v119 quad_perm:[1,0,3,2] row_mask:0xf bank_mask:0xf bound_ctrl:1
	s_nop 0
	ds_read_b128 v[124:127], v90 offset:0x1c00
	v_add_f32_dpp v118, v118, v118 quad_perm:[2,3,0,1] row_mask:0xf bank_mask:0xf bound_ctrl:1
	s_nop 0
	ds_write2_b32 v93, v1, v119 offset0:72 offset1:108
	v_add_f32_dpp v118, v118, v118 row_half_mirror row_mask:0xf bank_mask:0xf bound_ctrl:1
	s_nop 0
	s_waitcnt lgkmcnt(4)
	v_add_f32_dpp v2, v118, v118 row_mirror row_mask:0xf bank_mask:0xf bound_ctrl:1
	v_add_f32_dpp v118, v118, v118 row_mirror row_mask:0xf bank_mask:0xf bound_ctrl:1
	s_nop 1
	v_permlane16_swap_b32_e32 v118, v2
	v_add_f32_e32 v118, v118, v2
	v_pk_fma_f32 v[52:53], v[106:107], v[118:119], v[54:55] op_sel_hi:[1,0,1]
	v_pk_mul_f32 v[0:1], v[52:53], v[4:5] op_sel_hi:[0,1]
	v_pk_mul_f32 v[10:11], v[108:109], v[10:11] op_sel_hi:[0,1]
	v_pk_fma_f32 v[0:1], v[52:53], v[6:7], v[0:1] op_sel:[1,0,0]
	v_pk_fma_f32 v[54:55], v[52:53], v[8:9], v[10:11]
	s_nop 0
	ds_read_b128 v[4:7], v90 offset:0x5e00
	v_add_f32_dpp v0, v0, v0 quad_perm:[1,0,3,2] row_mask:0xf bank_mask:0xf bound_ctrl:1
	v_add_f32_dpp v1, v1, v1 quad_perm:[1,0,3,2] row_mask:0xf bank_mask:0xf bound_ctrl:1
	s_nop 0
	ds_read_b128 v[8:11], v90 offset:0x1e00
	v_add_f32_dpp v0, v0, v0 quad_perm:[2,3,0,1] row_mask:0xf bank_mask:0xf bound_ctrl:1
	s_nop 0
	ds_read2st64_b32 v[110:111], v89 offset0:206 offset1:207
	ds_read2st64_b64 v[104:107], v88 offset0:78 offset1:79
	v_add_f32_dpp v0, v0, v0 row_half_mirror row_mask:0xf bank_mask:0xf bound_ctrl:1
	s_nop 0
	s_waitcnt lgkmcnt(7)
	v_add_f32_dpp v2, v0, v0 row_mirror row_mask:0xf bank_mask:0xf bound_ctrl:1
	v_add_f32_dpp v0, v0, v0 row_mirror row_mask:0xf bank_mask:0xf bound_ctrl:1
	s_nop 1
	v_permlane16_swap_b32_e32 v0, v2
	v_add_f32_e32 v0, v0, v2
	v_pk_fma_f32 v[52:53], v[100:101], v[0:1], v[54:55] op_sel_hi:[1,0,1]
	v_pk_mul_f32 v[118:119], v[52:53], v[112:113] op_sel_hi:[0,1]
	v_pk_mul_f32 v[98:99], v[108:109], v[98:99] op_sel:[1,0]
	v_pk_fma_f32 v[118:119], v[52:53], v[114:115], v[118:119] op_sel:[1,0,0]
	v_pk_fma_f32 v[54:55], v[52:53], v[96:97], v[98:99]
	s_nop 0
	ds_read_b128 v[112:115], v90 offset:0x6000
	v_add_f32_dpp v118, v118, v118 quad_perm:[1,0,3,2] row_mask:0xf bank_mask:0xf bound_ctrl:1
	v_add_f32_dpp v119, v119, v119 quad_perm:[1,0,3,2] row_mask:0xf bank_mask:0xf bound_ctrl:1
	s_nop 0
	ds_read_b128 v[96:99], v90 offset:0x2000
	v_add_f32_dpp v118, v118, v118 quad_perm:[2,3,0,1] row_mask:0xf bank_mask:0xf bound_ctrl:1
	s_nop 0
	ds_write2_b32 v93, v1, v119 offset0:144 offset1:180
	v_add_f32_dpp v118, v118, v118 row_half_mirror row_mask:0xf bank_mask:0xf bound_ctrl:1
	s_nop 0
	s_waitcnt lgkmcnt(4)
	v_add_f32_dpp v2, v118, v118 row_mirror row_mask:0xf bank_mask:0xf bound_ctrl:1
	v_add_f32_dpp v118, v118, v118 row_mirror row_mask:0xf bank_mask:0xf bound_ctrl:1
	s_nop 1
	v_permlane16_swap_b32_e32 v118, v2
	v_add_f32_e32 v118, v118, v2
	v_pk_fma_f32 v[52:53], v[102:103], v[118:119], v[54:55] op_sel_hi:[1,0,1]
	v_pk_mul_f32 v[0:1], v[52:53], v[120:121] op_sel_hi:[0,1]
	v_pk_mul_f32 v[126:127], v[110:111], v[126:127] op_sel_hi:[0,1]
	v_pk_fma_f32 v[0:1], v[52:53], v[122:123], v[0:1] op_sel:[1,0,0]
	v_pk_fma_f32 v[54:55], v[52:53], v[124:125], v[126:127]
	s_nop 0
	ds_read_b128 v[120:123], v90 offset:0x6200
	v_add_f32_dpp v0, v0, v0 quad_perm:[1,0,3,2] row_mask:0xf bank_mask:0xf bound_ctrl:1
	v_add_f32_dpp v1, v1, v1 quad_perm:[1,0,3,2] row_mask:0xf bank_mask:0xf bound_ctrl:1
	s_nop 0
	ds_read_b128 v[124:127], v90 offset:0x2200
	v_add_f32_dpp v0, v0, v0 quad_perm:[2,3,0,1] row_mask:0xf bank_mask:0xf bound_ctrl:1
	s_nop 0
	ds_read2st64_b32 v[108:109], v89 offset0:208 offset1:209
	ds_read2st64_b64 v[100:103], v88 offset0:80 offset1:81
	v_add_f32_dpp v0, v0, v0 row_half_mirror row_mask:0xf bank_mask:0xf bound_ctrl:1
	s_nop 0
	s_waitcnt lgkmcnt(7)
	v_add_f32_dpp v2, v0, v0 row_mirror row_mask:0xf bank_mask:0xf bound_ctrl:1
	v_add_f32_dpp v0, v0, v0 row_mirror row_mask:0xf bank_mask:0xf bound_ctrl:1
	s_nop 1
	v_permlane16_swap_b32_e32 v0, v2
	v_add_f32_e32 v0, v0, v2
	v_pk_fma_f32 v[52:53], v[104:105], v[0:1], v[54:55] op_sel_hi:[1,0,1]
	v_pk_mul_f32 v[118:119], v[52:53], v[4:5] op_sel_hi:[0,1]
	v_pk_mul_f32 v[10:11], v[110:111], v[10:11] op_sel:[1,0]
	v_pk_fma_f32 v[118:119], v[52:53], v[6:7], v[118:119] op_sel:[1,0,0]
	v_pk_fma_f32 v[54:55], v[52:53], v[8:9], v[10:11]
	s_nop 0
	ds_read_b128 v[4:7], v90 offset:0x6400
	v_add_f32_dpp v118, v118, v118 quad_perm:[1,0,3,2] row_mask:0xf bank_mask:0xf bound_ctrl:1
	v_add_f32_dpp v119, v119, v119 quad_perm:[1,0,3,2] row_mask:0xf bank_mask:0xf bound_ctrl:1
	s_nop 0
	ds_read_b128 v[8:11], v90 offset:0x2400
	v_add_f32_dpp v118, v118, v118 quad_perm:[2,3,0,1] row_mask:0xf bank_mask:0xf bound_ctrl:1
	s_nop 0
	ds_write2_b32 v93, v1, v119 offset0:216 offset1:252
	v_add_f32_dpp v118, v118, v118 row_half_mirror row_mask:0xf bank_mask:0xf bound_ctrl:1
	s_nop 0
	s_waitcnt lgkmcnt(4)
	v_add_f32_dpp v2, v118, v118 row_mirror row_mask:0xf bank_mask:0xf bound_ctrl:1
	v_add_f32_dpp v118, v118, v118 row_mirror row_mask:0xf bank_mask:0xf bound_ctrl:1
	s_nop 1
	v_permlane16_swap_b32_e32 v118, v2
	v_add_f32_e32 v118, v118, v2
	v_pk_fma_f32 v[52:53], v[106:107], v[118:119], v[54:55] op_sel_hi:[1,0,1]
	s_cmp_eq_u32 s88, 0x800000
	s_cbranch_scc1 .LBB0_684
	v_pk_mul_f32 v[0:1], v[52:53], v[112:113] op_sel_hi:[0,1]
	v_pk_mul_f32 v[98:99], v[108:109], v[98:99] op_sel_hi:[0,1]
	v_pk_fma_f32 v[0:1], v[52:53], v[114:115], v[0:1] op_sel:[1,0,0]
	v_pk_fma_f32 v[54:55], v[52:53], v[96:97], v[98:99]
	s_nop 0
	ds_read_b128 v[112:115], v90 offset:0x6600
	v_add_f32_dpp v0, v0, v0 quad_perm:[1,0,3,2] row_mask:0xf bank_mask:0xf bound_ctrl:1
	v_add_f32_dpp v1, v1, v1 quad_perm:[1,0,3,2] row_mask:0xf bank_mask:0xf bound_ctrl:1
	s_nop 0
	ds_read_b128 v[96:99], v90 offset:0x2600
	v_add_f32_dpp v0, v0, v0 quad_perm:[2,3,0,1] row_mask:0xf bank_mask:0xf bound_ctrl:1
	s_nop 0
	ds_read2st64_b32 v[110:111], v89 offset0:210 offset1:211
	ds_read2st64_b64 v[104:107], v88 offset0:82 offset1:83
	v_add_f32_dpp v0, v0, v0 row_half_mirror row_mask:0xf bank_mask:0xf bound_ctrl:1
	v_add_u32_e32 v93, 0x480, v93
	s_waitcnt lgkmcnt(7)
	v_add_f32_dpp v2, v0, v0 row_mirror row_mask:0xf bank_mask:0xf bound_ctrl:1
	v_add_f32_dpp v0, v0, v0 row_mirror row_mask:0xf bank_mask:0xf bound_ctrl:1
	s_nop 1
	v_permlane16_swap_b32_e32 v0, v2
	v_add_f32_e32 v0, v0, v2
	v_pk_fma_f32 v[52:53], v[100:101], v[0:1], v[54:55] op_sel_hi:[1,0,1]
	v_pk_mul_f32 v[118:119], v[52:53], v[120:121] op_sel_hi:[0,1]
	v_pk_mul_f32 v[126:127], v[108:109], v[126:127] op_sel:[1,0]
	v_pk_fma_f32 v[118:119], v[52:53], v[122:123], v[118:119] op_sel:[1,0,0]
	v_pk_fma_f32 v[54:55], v[52:53], v[124:125], v[126:127]
	s_nop 0
	ds_read_b128 v[120:123], v90 offset:0x6800
	v_add_f32_dpp v118, v118, v118 quad_perm:[1,0,3,2] row_mask:0xf bank_mask:0xf bound_ctrl:1
	v_add_f32_dpp v119, v119, v119 quad_perm:[1,0,3,2] row_mask:0xf bank_mask:0xf bound_ctrl:1
	s_nop 0
	ds_read_b128 v[124:127], v90 offset:0x2800
	v_add_f32_dpp v118, v118, v118 quad_perm:[2,3,0,1] row_mask:0xf bank_mask:0xf bound_ctrl:1
	s_nop 0
	ds_write2_b32 v93, v1, v119 offset0:0 offset1:36
	v_add_f32_dpp v118, v118, v118 row_half_mirror row_mask:0xf bank_mask:0xf bound_ctrl:1
	s_nop 0
	s_waitcnt lgkmcnt(4)
	v_add_f32_dpp v2, v118, v118 row_mirror row_mask:0xf bank_mask:0xf bound_ctrl:1
	v_add_f32_dpp v118, v118, v118 row_mirror row_mask:0xf bank_mask:0xf bound_ctrl:1
	s_nop 1
	v_permlane16_swap_b32_e32 v118, v2
	v_add_f32_e32 v118, v118, v2
	v_pk_fma_f32 v[52:53], v[102:103], v[118:119], v[54:55] op_sel_hi:[1,0,1]
	v_pk_mul_f32 v[0:1], v[52:53], v[4:5] op_sel_hi:[0,1]
	v_pk_mul_f32 v[10:11], v[110:111], v[10:11] op_sel_hi:[0,1]
	v_pk_fma_f32 v[0:1], v[52:53], v[6:7], v[0:1] op_sel:[1,0,0]
	v_pk_fma_f32 v[54:55], v[52:53], v[8:9], v[10:11]
	s_nop 0
	ds_read_b128 v[4:7], v90 offset:0x6a00
	v_add_f32_dpp v0, v0, v0 quad_perm:[1,0,3,2] row_mask:0xf bank_mask:0xf bound_ctrl:1
	v_add_f32_dpp v1, v1, v1 quad_perm:[1,0,3,2] row_mask:0xf bank_mask:0xf bound_ctrl:1
	s_nop 0
	ds_read_b128 v[8:11], v90 offset:0x2a00
	v_add_f32_dpp v0, v0, v0 quad_perm:[2,3,0,1] row_mask:0xf bank_mask:0xf bound_ctrl:1
	s_nop 0
	ds_read2st64_b32 v[108:109], v89 offset0:212 offset1:213
	ds_read2st64_b64 v[100:103], v88 offset0:84 offset1:85
	v_add_f32_dpp v0, v0, v0 row_half_mirror row_mask:0xf bank_mask:0xf bound_ctrl:1
	s_nop 0
	s_waitcnt lgkmcnt(7)
	v_add_f32_dpp v2, v0, v0 row_mirror row_mask:0xf bank_mask:0xf bound_ctrl:1
	v_add_f32_dpp v0, v0, v0 row_mirror row_mask:0xf bank_mask:0xf bound_ctrl:1
	s_nop 1
	v_permlane16_swap_b32_e32 v0, v2
	v_add_f32_e32 v0, v0, v2
	v_pk_fma_f32 v[52:53], v[104:105], v[0:1], v[54:55] op_sel_hi:[1,0,1]
	v_pk_mul_f32 v[118:119], v[52:53], v[112:113] op_sel_hi:[0,1]
	v_pk_mul_f32 v[98:99], v[110:111], v[98:99] op_sel:[1,0]
	v_pk_fma_f32 v[118:119], v[52:53], v[114:115], v[118:119] op_sel:[1,0,0]
	v_pk_fma_f32 v[54:55], v[52:53], v[96:97], v[98:99]
	s_nop 0
	ds_read_b128 v[112:115], v90 offset:0x6c00
	v_add_f32_dpp v118, v118, v118 quad_perm:[1,0,3,2] row_mask:0xf bank_mask:0xf bound_ctrl:1
	v_add_f32_dpp v119, v119, v119 quad_perm:[1,0,3,2] row_mask:0xf bank_mask:0xf bound_ctrl:1
	s_nop 0
	ds_read_b128 v[96:99], v90 offset:0x2c00
	v_add_f32_dpp v118, v118, v118 quad_perm:[2,3,0,1] row_mask:0xf bank_mask:0xf bound_ctrl:1
	s_nop 0
	ds_write2_b32 v93, v1, v119 offset0:72 offset1:108
	v_add_f32_dpp v118, v118, v118 row_half_mirror row_mask:0xf bank_mask:0xf bound_ctrl:1
	s_nop 0
	s_waitcnt lgkmcnt(4)
	v_add_f32_dpp v2, v118, v118 row_mirror row_mask:0xf bank_mask:0xf bound_ctrl:1
	v_add_f32_dpp v118, v118, v118 row_mirror row_mask:0xf bank_mask:0xf bound_ctrl:1
	s_nop 1
	v_permlane16_swap_b32_e32 v118, v2
	v_add_f32_e32 v118, v118, v2
	v_pk_fma_f32 v[52:53], v[106:107], v[118:119], v[54:55] op_sel_hi:[1,0,1]
	v_pk_mul_f32 v[0:1], v[52:53], v[120:121] op_sel_hi:[0,1]
	v_pk_mul_f32 v[126:127], v[108:109], v[126:127] op_sel_hi:[0,1]
	v_pk_fma_f32 v[0:1], v[52:53], v[122:123], v[0:1] op_sel:[1,0,0]
	v_pk_fma_f32 v[54:55], v[52:53], v[124:125], v[126:127]
	s_nop 0
	ds_read_b128 v[120:123], v90 offset:0x6e00
	v_add_f32_dpp v0, v0, v0 quad_perm:[1,0,3,2] row_mask:0xf bank_mask:0xf bound_ctrl:1
	v_add_f32_dpp v1, v1, v1 quad_perm:[1,0,3,2] row_mask:0xf bank_mask:0xf bound_ctrl:1
	s_nop 0
	ds_read_b128 v[124:127], v90 offset:0x2e00
	v_add_f32_dpp v0, v0, v0 quad_perm:[2,3,0,1] row_mask:0xf bank_mask:0xf bound_ctrl:1
	s_nop 0
	ds_read2st64_b32 v[110:111], v89 offset0:214 offset1:215
	ds_read2st64_b64 v[104:107], v88 offset0:86 offset1:87
	v_add_f32_dpp v0, v0, v0 row_half_mirror row_mask:0xf bank_mask:0xf bound_ctrl:1
	s_nop 0
	s_waitcnt lgkmcnt(7)
	v_add_f32_dpp v2, v0, v0 row_mirror row_mask:0xf bank_mask:0xf bound_ctrl:1
	v_add_f32_dpp v0, v0, v0 row_mirror row_mask:0xf bank_mask:0xf bound_ctrl:1
	s_nop 1
	v_permlane16_swap_b32_e32 v0, v2
	v_add_f32_e32 v0, v0, v2
	v_pk_fma_f32 v[52:53], v[100:101], v[0:1], v[54:55] op_sel_hi:[1,0,1]
	v_pk_mul_f32 v[118:119], v[52:53], v[4:5] op_sel_hi:[0,1]
	v_pk_mul_f32 v[10:11], v[108:109], v[10:11] op_sel:[1,0]
	v_pk_fma_f32 v[118:119], v[52:53], v[6:7], v[118:119] op_sel:[1,0,0]
	v_pk_fma_f32 v[54:55], v[52:53], v[8:9], v[10:11]
	s_nop 0
	ds_read_b128 v[4:7], v90 offset:0x7000
	v_add_f32_dpp v118, v118, v118 quad_perm:[1,0,3,2] row_mask:0xf bank_mask:0xf bound_ctrl:1
	v_add_f32_dpp v119, v119, v119 quad_perm:[1,0,3,2] row_mask:0xf bank_mask:0xf bound_ctrl:1
	s_nop 0
	ds_read_b128 v[8:11], v90 offset:0x3000
	v_add_f32_dpp v118, v118, v118 quad_perm:[2,3,0,1] row_mask:0xf bank_mask:0xf bound_ctrl:1
	s_nop 0
	ds_write2_b32 v93, v1, v119 offset0:144 offset1:180
	v_add_f32_dpp v118, v118, v118 row_half_mirror row_mask:0xf bank_mask:0xf bound_ctrl:1
	s_nop 0
	s_waitcnt lgkmcnt(4)
	v_add_f32_dpp v2, v118, v118 row_mirror row_mask:0xf bank_mask:0xf bound_ctrl:1
	v_add_f32_dpp v118, v118, v118 row_mirror row_mask:0xf bank_mask:0xf bound_ctrl:1
	s_nop 1
	v_permlane16_swap_b32_e32 v118, v2
	v_add_f32_e32 v118, v118, v2
	v_pk_fma_f32 v[52:53], v[102:103], v[118:119], v[54:55] op_sel_hi:[1,0,1]
	v_pk_mul_f32 v[0:1], v[52:53], v[112:113] op_sel_hi:[0,1]
	v_pk_mul_f32 v[98:99], v[110:111], v[98:99] op_sel_hi:[0,1]
	v_pk_fma_f32 v[0:1], v[52:53], v[114:115], v[0:1] op_sel:[1,0,0]
	v_pk_fma_f32 v[54:55], v[52:53], v[96:97], v[98:99]
	s_nop 0
	ds_read_b128 v[112:115], v90 offset:0x7200
	v_add_f32_dpp v0, v0, v0 quad_perm:[1,0,3,2] row_mask:0xf bank_mask:0xf bound_ctrl:1
	v_add_f32_dpp v1, v1, v1 quad_perm:[1,0,3,2] row_mask:0xf bank_mask:0xf bound_ctrl:1
	s_nop 0
	ds_read_b128 v[96:99], v90 offset:0x3200
	v_add_f32_dpp v0, v0, v0 quad_perm:[2,3,0,1] row_mask:0xf bank_mask:0xf bound_ctrl:1
	s_nop 0
	ds_read2st64_b32 v[108:109], v89 offset0:216 offset1:217
	ds_read2st64_b64 v[100:103], v88 offset0:88 offset1:89
	v_add_f32_dpp v0, v0, v0 row_half_mirror row_mask:0xf bank_mask:0xf bound_ctrl:1
	s_nop 0
	s_waitcnt lgkmcnt(7)
	v_add_f32_dpp v2, v0, v0 row_mirror row_mask:0xf bank_mask:0xf bound_ctrl:1
	v_add_f32_dpp v0, v0, v0 row_mirror row_mask:0xf bank_mask:0xf bound_ctrl:1
	s_nop 1
	v_permlane16_swap_b32_e32 v0, v2
	v_add_f32_e32 v0, v0, v2
	v_pk_fma_f32 v[52:53], v[104:105], v[0:1], v[54:55] op_sel_hi:[1,0,1]
	v_pk_mul_f32 v[118:119], v[52:53], v[120:121] op_sel_hi:[0,1]
	v_pk_mul_f32 v[126:127], v[110:111], v[126:127] op_sel:[1,0]
	v_pk_fma_f32 v[118:119], v[52:53], v[122:123], v[118:119] op_sel:[1,0,0]
	v_pk_fma_f32 v[54:55], v[52:53], v[124:125], v[126:127]
	s_nop 0
	ds_read_b128 v[120:123], v90 offset:0x7400
	v_add_f32_dpp v118, v118, v118 quad_perm:[1,0,3,2] row_mask:0xf bank_mask:0xf bound_ctrl:1
	v_add_f32_dpp v119, v119, v119 quad_perm:[1,0,3,2] row_mask:0xf bank_mask:0xf bound_ctrl:1
	s_nop 0
	ds_read_b128 v[124:127], v90 offset:0x3400
	v_add_f32_dpp v118, v118, v118 quad_perm:[2,3,0,1] row_mask:0xf bank_mask:0xf bound_ctrl:1
	s_nop 0
	ds_write2_b32 v93, v1, v119 offset0:216 offset1:252
	v_add_f32_dpp v118, v118, v118 row_half_mirror row_mask:0xf bank_mask:0xf bound_ctrl:1
	s_nop 0
	s_waitcnt lgkmcnt(4)
	v_add_f32_dpp v2, v118, v118 row_mirror row_mask:0xf bank_mask:0xf bound_ctrl:1
	v_add_f32_dpp v118, v118, v118 row_mirror row_mask:0xf bank_mask:0xf bound_ctrl:1
	s_nop 1
	v_permlane16_swap_b32_e32 v118, v2
	v_add_f32_e32 v118, v118, v2
	v_pk_fma_f32 v[52:53], v[106:107], v[118:119], v[54:55] op_sel_hi:[1,0,1]
	v_pk_mul_f32 v[0:1], v[52:53], v[4:5] op_sel_hi:[0,1]
	v_pk_mul_f32 v[10:11], v[108:109], v[10:11] op_sel_hi:[0,1]
	v_pk_fma_f32 v[0:1], v[52:53], v[6:7], v[0:1] op_sel:[1,0,0]
	v_pk_fma_f32 v[54:55], v[52:53], v[8:9], v[10:11]
	s_nop 0
	ds_read_b128 v[4:7], v90 offset:0x7600
	v_add_f32_dpp v0, v0, v0 quad_perm:[1,0,3,2] row_mask:0xf bank_mask:0xf bound_ctrl:1
	v_add_f32_dpp v1, v1, v1 quad_perm:[1,0,3,2] row_mask:0xf bank_mask:0xf bound_ctrl:1
	s_nop 0
	ds_read_b128 v[8:11], v90 offset:0x3600
	v_add_f32_dpp v0, v0, v0 quad_perm:[2,3,0,1] row_mask:0xf bank_mask:0xf bound_ctrl:1
	s_nop 0
	ds_read2st64_b32 v[110:111], v89 offset0:218 offset1:219
	ds_read2st64_b64 v[104:107], v88 offset0:90 offset1:91
	v_add_f32_dpp v0, v0, v0 row_half_mirror row_mask:0xf bank_mask:0xf bound_ctrl:1
	v_add_u32_e32 v93, 0x480, v93
	s_waitcnt lgkmcnt(7)
	v_add_f32_dpp v2, v0, v0 row_mirror row_mask:0xf bank_mask:0xf bound_ctrl:1
	v_add_f32_dpp v0, v0, v0 row_mirror row_mask:0xf bank_mask:0xf bound_ctrl:1
	s_nop 1
	v_permlane16_swap_b32_e32 v0, v2
	v_add_f32_e32 v0, v0, v2
	v_pk_fma_f32 v[52:53], v[100:101], v[0:1], v[54:55] op_sel_hi:[1,0,1]
	v_pk_mul_f32 v[118:119], v[52:53], v[112:113] op_sel_hi:[0,1]
	v_pk_mul_f32 v[98:99], v[108:109], v[98:99] op_sel:[1,0]
	v_pk_fma_f32 v[118:119], v[52:53], v[114:115], v[118:119] op_sel:[1,0,0]
	v_pk_fma_f32 v[54:55], v[52:53], v[96:97], v[98:99]
	s_nop 0
	ds_read_b128 v[112:115], v90 offset:0x7800
	v_add_f32_dpp v118, v118, v118 quad_perm:[1,0,3,2] row_mask:0xf bank_mask:0xf bound_ctrl:1
	v_add_f32_dpp v119, v119, v119 quad_perm:[1,0,3,2] row_mask:0xf bank_mask:0xf bound_ctrl:1
	s_nop 0
	ds_read_b128 v[96:99], v90 offset:0x3800
	v_add_f32_dpp v118, v118, v118 quad_perm:[2,3,0,1] row_mask:0xf bank_mask:0xf bound_ctrl:1
	s_nop 0
	ds_write2_b32 v93, v1, v119 offset0:0 offset1:36
	v_add_f32_dpp v118, v118, v118 row_half_mirror row_mask:0xf bank_mask:0xf bound_ctrl:1
	s_nop 0
	s_waitcnt lgkmcnt(4)
	v_add_f32_dpp v2, v118, v118 row_mirror row_mask:0xf bank_mask:0xf bound_ctrl:1
	v_add_f32_dpp v118, v118, v118 row_mirror row_mask:0xf bank_mask:0xf bound_ctrl:1
	s_nop 1
	v_permlane16_swap_b32_e32 v118, v2
	v_add_f32_e32 v118, v118, v2
	v_pk_fma_f32 v[52:53], v[102:103], v[118:119], v[54:55] op_sel_hi:[1,0,1]
	v_pk_mul_f32 v[0:1], v[52:53], v[120:121] op_sel_hi:[0,1]
	v_pk_mul_f32 v[126:127], v[110:111], v[126:127] op_sel_hi:[0,1]
	v_pk_fma_f32 v[0:1], v[52:53], v[122:123], v[0:1] op_sel:[1,0,0]
	v_pk_fma_f32 v[54:55], v[52:53], v[124:125], v[126:127]
	s_nop 0
	ds_read_b128 v[120:123], v90 offset:0x7a00
	v_add_f32_dpp v0, v0, v0 quad_perm:[1,0,3,2] row_mask:0xf bank_mask:0xf bound_ctrl:1
	v_add_f32_dpp v1, v1, v1 quad_perm:[1,0,3,2] row_mask:0xf bank_mask:0xf bound_ctrl:1
	s_nop 0
	ds_read_b128 v[124:127], v90 offset:0x3a00
	v_add_f32_dpp v0, v0, v0 quad_perm:[2,3,0,1] row_mask:0xf bank_mask:0xf bound_ctrl:1
	s_nop 0
	ds_read2st64_b32 v[108:109], v89 offset0:220 offset1:221
	ds_read2st64_b64 v[100:103], v88 offset0:92 offset1:93
	v_add_f32_dpp v0, v0, v0 row_half_mirror row_mask:0xf bank_mask:0xf bound_ctrl:1
	s_nop 0
	s_waitcnt lgkmcnt(7)
	v_add_f32_dpp v2, v0, v0 row_mirror row_mask:0xf bank_mask:0xf bound_ctrl:1
	v_add_f32_dpp v0, v0, v0 row_mirror row_mask:0xf bank_mask:0xf bound_ctrl:1
	s_nop 1
	v_permlane16_swap_b32_e32 v0, v2
	v_add_f32_e32 v0, v0, v2
	v_pk_fma_f32 v[52:53], v[104:105], v[0:1], v[54:55] op_sel_hi:[1,0,1]
	v_pk_mul_f32 v[118:119], v[52:53], v[4:5] op_sel_hi:[0,1]
	v_pk_mul_f32 v[10:11], v[110:111], v[10:11] op_sel:[1,0]
	v_pk_fma_f32 v[118:119], v[52:53], v[6:7], v[118:119] op_sel:[1,0,0]
	v_pk_fma_f32 v[54:55], v[52:53], v[8:9], v[10:11]
	s_nop 0
	ds_read_b128 v[4:7], v90 offset:0x7c00
	v_add_f32_dpp v118, v118, v118 quad_perm:[1,0,3,2] row_mask:0xf bank_mask:0xf bound_ctrl:1
	v_add_f32_dpp v119, v119, v119 quad_perm:[1,0,3,2] row_mask:0xf bank_mask:0xf bound_ctrl:1
	s_nop 0
	ds_read_b128 v[8:11], v90 offset:0x3c00
	v_add_f32_dpp v118, v118, v118 quad_perm:[2,3,0,1] row_mask:0xf bank_mask:0xf bound_ctrl:1
	s_nop 0
	ds_write2_b32 v93, v1, v119 offset0:72 offset1:108
	v_add_f32_dpp v118, v118, v118 row_half_mirror row_mask:0xf bank_mask:0xf bound_ctrl:1
	s_nop 0
	s_waitcnt lgkmcnt(4)
	v_add_f32_dpp v2, v118, v118 row_mirror row_mask:0xf bank_mask:0xf bound_ctrl:1
	v_add_f32_dpp v118, v118, v118 row_mirror row_mask:0xf bank_mask:0xf bound_ctrl:1
	s_nop 1
	v_permlane16_swap_b32_e32 v118, v2
	v_add_f32_e32 v118, v118, v2
	v_pk_fma_f32 v[52:53], v[106:107], v[118:119], v[54:55] op_sel_hi:[1,0,1]
	v_pk_mul_f32 v[0:1], v[52:53], v[112:113] op_sel_hi:[0,1]
	v_pk_mul_f32 v[98:99], v[108:109], v[98:99] op_sel_hi:[0,1]
	v_pk_fma_f32 v[0:1], v[52:53], v[114:115], v[0:1] op_sel:[1,0,0]
	v_pk_fma_f32 v[54:55], v[52:53], v[96:97], v[98:99]
	s_nop 0
	ds_read_b128 v[112:115], v90 offset:0x7e00
	v_add_f32_dpp v0, v0, v0 quad_perm:[1,0,3,2] row_mask:0xf bank_mask:0xf bound_ctrl:1
	v_add_f32_dpp v1, v1, v1 quad_perm:[1,0,3,2] row_mask:0xf bank_mask:0xf bound_ctrl:1
	s_nop 0
	ds_read_b128 v[96:99], v90 offset:0x3e00
	v_add_f32_dpp v0, v0, v0 quad_perm:[2,3,0,1] row_mask:0xf bank_mask:0xf bound_ctrl:1
	s_nop 0
	ds_read2st64_b32 v[110:111], v89 offset0:222 offset1:223
	ds_read2st64_b64 v[104:107], v88 offset0:94 offset1:95
	v_add_f32_dpp v0, v0, v0 row_half_mirror row_mask:0xf bank_mask:0xf bound_ctrl:1
	s_nop 0
	s_waitcnt lgkmcnt(7)
	v_add_f32_dpp v2, v0, v0 row_mirror row_mask:0xf bank_mask:0xf bound_ctrl:1
	v_add_f32_dpp v0, v0, v0 row_mirror row_mask:0xf bank_mask:0xf bound_ctrl:1
	s_nop 1
	v_permlane16_swap_b32_e32 v0, v2
	v_add_f32_e32 v0, v0, v2
	v_pk_fma_f32 v[52:53], v[100:101], v[0:1], v[54:55] op_sel_hi:[1,0,1]
	v_pk_mul_f32 v[118:119], v[52:53], v[120:121] op_sel_hi:[0,1]
	v_pk_mul_f32 v[126:127], v[108:109], v[126:127] op_sel:[1,0]
	v_pk_fma_f32 v[118:119], v[52:53], v[122:123], v[118:119] op_sel:[1,0,0]
	v_pk_fma_f32 v[54:55], v[52:53], v[124:125], v[126:127]
	s_nop 0
	s_nop 0
	v_add_f32_dpp v118, v118, v118 quad_perm:[1,0,3,2] row_mask:0xf bank_mask:0xf bound_ctrl:1
	v_add_f32_dpp v119, v119, v119 quad_perm:[1,0,3,2] row_mask:0xf bank_mask:0xf bound_ctrl:1
	s_nop 0
	s_nop 0
	v_add_f32_dpp v118, v118, v118 quad_perm:[2,3,0,1] row_mask:0xf bank_mask:0xf bound_ctrl:1
	s_nop 0
	ds_write2_b32 v93, v1, v119 offset0:144 offset1:180
	v_add_f32_dpp v118, v118, v118 row_half_mirror row_mask:0xf bank_mask:0xf bound_ctrl:1
	s_nop 0
	s_waitcnt lgkmcnt(2)
	v_add_f32_dpp v2, v118, v118 row_mirror row_mask:0xf bank_mask:0xf bound_ctrl:1
	v_add_f32_dpp v118, v118, v118 row_mirror row_mask:0xf bank_mask:0xf bound_ctrl:1
	s_nop 1
	v_permlane16_swap_b32_e32 v118, v2
	v_add_f32_e32 v118, v118, v2
	v_pk_fma_f32 v[52:53], v[102:103], v[118:119], v[54:55] op_sel_hi:[1,0,1]
	v_pk_mul_f32 v[0:1], v[52:53], v[4:5] op_sel_hi:[0,1]
	v_pk_mul_f32 v[10:11], v[110:111], v[10:11] op_sel_hi:[0,1]
	v_pk_fma_f32 v[0:1], v[52:53], v[6:7], v[0:1] op_sel:[1,0,0]
	v_pk_fma_f32 v[54:55], v[52:53], v[8:9], v[10:11]
	s_nop 0
	s_nop 0
	v_add_f32_dpp v0, v0, v0 quad_perm:[1,0,3,2] row_mask:0xf bank_mask:0xf bound_ctrl:1
	v_add_f32_dpp v1, v1, v1 quad_perm:[1,0,3,2] row_mask:0xf bank_mask:0xf bound_ctrl:1
	s_nop 0
	s_nop 0
	v_add_f32_dpp v0, v0, v0 quad_perm:[2,3,0,1] row_mask:0xf bank_mask:0xf bound_ctrl:1
	s_nop 0
	s_nop 0
	v_add_f32_dpp v0, v0, v0 row_half_mirror row_mask:0xf bank_mask:0xf bound_ctrl:1
	s_nop 0
	s_waitcnt lgkmcnt(1)
	v_add_f32_dpp v2, v0, v0 row_mirror row_mask:0xf bank_mask:0xf bound_ctrl:1
	v_add_f32_dpp v0, v0, v0 row_mirror row_mask:0xf bank_mask:0xf bound_ctrl:1
	s_nop 1
	v_permlane16_swap_b32_e32 v0, v2
	v_add_f32_e32 v0, v0, v2
	v_pk_fma_f32 v[52:53], v[104:105], v[0:1], v[54:55] op_sel_hi:[1,0,1]
	v_pk_mul_f32 v[118:119], v[52:53], v[112:113] op_sel_hi:[0,1]
	v_pk_mul_f32 v[98:99], v[110:111], v[98:99] op_sel:[1,0]
	v_pk_fma_f32 v[118:119], v[52:53], v[114:115], v[118:119] op_sel:[1,0,0]
	v_pk_fma_f32 v[54:55], v[52:53], v[96:97], v[98:99]
	s_nop 0
	s_nop 0
	v_add_f32_dpp v118, v118, v118 quad_perm:[1,0,3,2] row_mask:0xf bank_mask:0xf bound_ctrl:1
	v_add_f32_dpp v119, v119, v119 quad_perm:[1,0,3,2] row_mask:0xf bank_mask:0xf bound_ctrl:1
	s_nop 0
	s_nop 0
	v_add_f32_dpp v118, v118, v118 quad_perm:[2,3,0,1] row_mask:0xf bank_mask:0xf bound_ctrl:1
	s_nop 0
	ds_write2_b32 v93, v1, v119 offset0:216 offset1:252
	v_add_f32_dpp v118, v118, v118 row_half_mirror row_mask:0xf bank_mask:0xf bound_ctrl:1
	s_nop 0
	s_nop 0
	v_add_f32_dpp v2, v118, v118 row_mirror row_mask:0xf bank_mask:0xf bound_ctrl:1
	v_add_f32_dpp v118, v118, v118 row_mirror row_mask:0xf bank_mask:0xf bound_ctrl:1
	s_nop 1
	v_permlane16_swap_b32_e32 v118, v2
	v_add_f32_e32 v118, v118, v2
	v_pk_fma_f32 v[52:53], v[106:107], v[118:119], v[54:55] op_sel_hi:[1,0,1]
